# attention queues: each wave drains only its own XCD queue (cross-XCD stealing loop cut to one pass, removes 7 serialized empty-queue pops per wave per phase), on top of k36
# baseline (speedup 1.0000x reference)
.LBB0_1488:
	s_add_i32 s2, s39, 1
	s_cmp_eq_u32 s2, 1
	s_cbranch_scc1 .LBB0_1644
